# P10-tail-PLE-units-260-263-moved-to-workgroups-168-171
# speedup vs baseline: 1.0034x; 1.0034x over previous
; template <class Epi, bool ALIGN_EPI = true, bool SP2 = true, bool QUARTER = false, class Sched = Order>
; __device__ __forceinline__ void gemm_phase(PG8_LAS unsigned char* lds, const Gemm g, const Sched& S, const Epi& E) {
;     ...
;     const int wid = __builtin_amdgcn_readfirstlane(tid >> 6), lane = tid & 63, wr = wid >> 2, wc = wid & 3, fr = lane & 15, fq = lane >> 4;
;     int K = g.K; asm volatile("" : "+s"(K));
;     const int nt = K / BK;
;     unsigned voffA[2], voffB[2];
; #pragma unroll
;     for (int i = 0; i < 2; ++i) { int R, C; stage_rc(tid * 16 + i * 8192, R, C); const int Rb = Epi::PERM ? ((R & ~31) + perm32(R & 31)) : R;
;         voffA[i] = (unsigned)(R * g.lda + C) * 2u; voffB[i] = (unsigned)(Rb * g.ldb + C) * 2u; }
;     const size_t kstep = (size_t)(BK * 2);
;     const size_t hstepA = (size_t)HALF * g.lda * 2, hstepB = (size_t)HALF * g.ldb * 2;
;     const size_t tstepA = 2 * hstepA, tstepB = 2 * hstepB;
;     const unsigned ldsw = (unsigned)wid * 1024u;
;     const int aoff = lds_byte(wr * 64 + fr, fq * 8), boff = lds_byte(wc * 32 + fr, fq * 8);
;     ...
;     Unit cur, nxt; int ui = 0;
;     if (!S.next(0, cur)) return;
;     f32x4 acc[2][2][4][2];
; #pragma unroll
;     for (int a = 0; a < 2; ++a)
; #pragma unroll
;         for (int b = 0; b < 2; ++b)
; #pragma unroll
;             for (int m = 0; m < 4; ++m)
; #pragma unroll
;                 for (int n = 0; n < 2; ++n) acc[a][b][m][n] = (f32x4){0.f, 0.f, 0.f, 0.f};
;     bf16x8 At[4][2], B0[2][2], B1[2][2];
; __global__ void __launch_bounds__(NWAVES * 64, 2) mk_fwd(Args args) {
;     ...
;           const int nb_ = (NUS + NUP) % G; const int nidle = nb_ ? G - nb_ : G, ci = nb_ ? bx - nb_ : bx;
;           const int nd_ = (nidle > 64) ? 32 : 0;
;           if (ci >= 0 && ci < nd_) { pg8::Gemm gd{HB, WDN, DFF, DFF, DFF, 0, 0}; EpiResid<true> Ed{nullptr, nullptr, XN, X2B, SS2};
;               pg8::Order Sd; Sd.init(MS / 256, 4, 1, nd_, ci, 0, MP / 256, 4); pg8::Unit uo;
;               for (int i = 0; Sd.next(i, uo); ++i) wait_panel(ctl + CW_PAN, uo.pm, (unsigned)(UPW / 256) * 8u, ctl + CW_PTMO);
;               pg8::gemm_phase<EpiResid<true>, true, true, true>(lds + RING_OFF, gd, Sd, Ed); }
;           else if (ci >= nd_) { pg8::Order So; So.init(NMT, 4, 1, nidle - nd_, ci - nd_, 0); pg8::gemm_phase(lds + RING_OFF, gp, So, Ep); } }
.LBB0_2706:
	s_abs_i32 s0, s94
	v_cvt_f32_u32_e32 v1, s0
	s_sub_i32 s1, 0, s0
	v_rcp_iflag_f32_e32 v1, v1
	s_nop 0
	v_mul_f32_e32 v1, 0x4f7ffffe, v1
	v_cvt_u32_f32_e32 v1, v1
	s_nop 0
	v_readfirstlane_b32 s2, v1
	s_mul_i32 s1, s1, s2
	s_mul_hi_u32 s1, s2, s1
	s_add_i32 s2, s2, s1
	s_mul_hi_u32 s1, s2, 0x5ac
	s_mul_i32 s1, s1, s0
	s_sub_i32 s1, 0x5ac, s1
	s_sub_i32 s2, s1, s0
	s_cmp_ge_u32 s1, s0
	s_cselect_b32 s1, s2, s1
	s_sub_i32 s2, s1, s0
	s_cmp_ge_u32 s1, s0
	s_cselect_b32 s0, s2, s1
	s_sub_i32 s4, s94, s0
	s_sub_i32 s23, s92, s0
	s_add_i32 s98, s23, 4
	s_cmp_lt_u32 s98, 4
	s_cselect_b32 s98, 0x128, 0
	s_add_i32 s23, s23, s98
	s_cmp_gt_i32 s4, 64
	s_cselect_b32 s33, 32, 0
	s_cmp_gt_i32 s23, -1
	s_cselect_b64 s[2:3], -1, 0
	s_cmp_ge_i32 s23, s33
	s_cselect_b64 s[0:1], -1, 0
	s_cmp_lt_i32 s23, s33
	s_cselect_b64 s[6:7], -1, 0
	s_and_b64 s[2:3], s[2:3], s[6:7]
	s_andn2_b64 vcc, exec, s[2:3]
	s_mov_b64 s[2:3], -1
	s_cbranch_vccz .LBB0_2726
	s_andn2_b64 vcc, exec, s[0:1]
	s_cbranch_vccnz .LBB0_2725
	s_sub_i32 s52, s23, s33
	v_mov_b32_e32 v11, v0
	s_movk_i32 s6, 0x100
	v_readfirstlane_b32 s3, v11
	s_cmpk_gt_i32 s52, 0x107
	s_cbranch_scc1 .LBB0_2725
	v_lshlrev_b32_e32 v1, 4, v11
	v_add_u32_e32 v2, 0x2000, v1
	v_ashrrev_i32_e32 v3, 31, v2
	v_lshrrev_b32_e32 v3, 22, v3
	v_add_u32_e32 v3, v2, v3
	v_ashrrev_i32_e32 v10, 10, v3
	v_mul_i32_i24_e32 v3, 0x400, v10
	v_sub_u32_e32 v2, v2, v3
	v_lshrrev_b32_e32 v3, 4, v2
	v_bitop3_b32 v2, v3, v2, 32 bitop3:0x6c
	v_ashrrev_i32_e32 v3, 31, v2
	v_lshrrev_b32_e32 v3, 26, v3
	v_add_u32_e32 v3, v2, v3
	v_lshlrev_b32_e32 v4, 3, v10
	v_ashrrev_i32_e32 v12, 6, v3
	v_and_b32_e32 v4, -16, v4
	v_add_u32_e32 v4, v12, v4
	v_and_b32_e32 v5, 3, v12
	s_mov_b32 s0, 0x7fffe0
	v_lshrrev_b32_e32 v6, 2, v4
	v_lshlrev_b32_e32 v7, 1, v4
	v_and_b32_e32 v3, 0xc0, v3
	v_and_or_b32 v5, v4, s0, v5
	v_and_b32_e32 v6, 4, v6
	v_and_b32_e32 v7, 24, v7
	v_sub_u32_e32 v2, v2, v3
	v_mov_b32_e32 v3, 1
	v_or3_b32 v5, v5, v6, v7
	v_lshlrev_b32_e32 v6, 5, v10
	v_ashrrev_i16_sdwa v2, v3, sext(v2) dst_sel:DWORD dst_unused:UNUSED_PAD src0_sel:DWORD src1_sel:BYTE_0
	v_and_b32_e32 v6, 32, v6
	v_bfe_i32 v13, v2, 0, 16
	v_add_lshl_u32 v2, v6, v13, 1
	v_lshl_add_u32 v130, v5, 9, v2
	v_lshl_add_u32 v132, v4, 9, v2
	v_bfe_i32 v2, v11, 27, 1
	v_lshrrev_b32_e32 v2, 22, v2
	v_add_u32_e32 v2, v1, v2
	v_and_b32_e32 v2, 0xfffffc00, v2
	v_sub_u32_e32 v1, v1, v2
	v_lshrrev_b32_e32 v2, 4, v1
	v_ashrrev_i32_e32 v4, 31, v11
	v_bitop3_b32 v1, v2, v1, 32 bitop3:0x6c
	v_lshrrev_b32_e32 v4, 26, v4
	v_ashrrev_i32_e32 v2, 31, v1
	v_add_u32_e32 v4, v11, v4
	s_ashr_i32 s5, s3, 6
	v_lshrrev_b32_e32 v2, 26, v2
	v_ashrrev_i32_e32 v15, 6, v4
	s_ashr_i32 s7, s3, 8
	s_lshl_b32 s53, s5, 10
	v_add_u32_e32 v2, v1, v2
	v_lshlrev_b32_e32 v4, 3, v15
	s_add_u32 s54, s40, 0xfa00000
	v_ashrrev_i32_e32 v14, 6, v2
	v_and_b32_e32 v4, -16, v4
	s_addc_u32 s55, s41, 0
	v_add_u32_e32 v4, v14, v4
	v_and_b32_e32 v5, 3, v14
	s_add_u32 s56, s40, 0x1300000
	v_and_or_b32 v5, v4, s0, v5
	s_sext_i32_i16 s0, s52
	s_addc_u32 s57, s41, 0
	s_bfe_u32 s0, s0, 0x3001c
	s_add_i32 s0, s52, s0
	s_sext_i32_i16 s1, s0
	s_and_b32 s0, s0, 0xfff8
	s_sub_i32 s0, s52, s0
	s_ashr_i32 s1, s1, 3
	s_sext_i32_i16 s2, s0
	s_cmp_lt_i32 s2, 0
	s_cselect_b32 s2, 34, 33
	s_mul_i32 s0, s0, s2
	s_add_i32 s0, s0, s1
	s_sext_i32_i16 s1, s0
	s_bfe_u32 s1, s1, 0x5001a
	s_add_i32 s1, s0, s1
	s_sext_i32_i16 s2, s1
	v_lshrrev_b32_e32 v6, 2, v4
	v_lshlrev_b32_e32 v7, 1, v4
	v_and_b32_e32 v2, 0xc0, v2
	s_ashr_i32 s2, s2, 5
	v_and_b32_e32 v6, 4, v6
	v_and_b32_e32 v7, 24, v7
	v_sub_u32_e32 v1, v1, v2
	s_lshl_b32 s12, s2, 3
	v_or3_b32 v5, v5, v6, v7
	v_lshlrev_b32_e32 v6, 5, v15
	v_ashrrev_i16_sdwa v1, v3, sext(v1) dst_sel:DWORD dst_unused:UNUSED_PAD src0_sel:DWORD src1_sel:BYTE_0
	s_sub_i32 s2, 0x42, s12
	s_and_b32 s1, s1, 0xffe0
	v_and_b32_e32 v6, 32, v6
	s_waitcnt vmcnt(0)
	v_bfe_i32 v16, v1, 0, 16
	s_min_u32 s13, s2, 8
	s_sub_i32 s16, s0, s1
	v_add_lshl_u32 v1, v6, v16, 1
	s_sext_i32_i16 s0, s16
	v_cvt_f32_ubyte0_e32 v3, s13
	v_lshl_add_u32 v134, v5, 9, v1
	v_cvt_f32_i32_e32 v2, s0
	v_rcp_iflag_f32_e32 v5, v3
	v_lshl_add_u32 v136, v4, 9, v1
	s_ashr_i32 s0, s0, 30
	s_or_b32 s2, s0, 1
	v_mul_f32_e32 v1, v2, v5
	v_trunc_f32_e32 v1, v1
	v_fma_f32 v2, -v1, v3, v2
	v_cvt_i32_f32_e32 v1, v1
	v_cmp_ge_f32_e64 s[0:1], |v2|, v3
	s_and_b64 s[0:1], s[0:1], exec
	s_cselect_b32 s0, s2, 0
	v_readfirstlane_b32 s1, v1
	s_add_i32 s2, s1, s0
	s_mul_i32 s0, s2, s13
	s_sub_i32 s0, s16, s0
	s_sext_i32_i8 s0, s0
	s_add_i32 s34, s12, s0
	s_ashr_i32 s35, s34, 31
	s_bfe_i64 s[12:13], s[2:3], 0x80000
	s_lshl_b64 s[0:1], s[34:35], 17
	s_lshl_b64 s[12:13], s[12:13], 17
	s_add_u32 s44, s56, s12
	s_addc_u32 s45, s57, s13
	s_add_i32 s35, s53, 0
	s_add_i32 m0, s35, 0x10000
	v_mov_b32_e32 v135, 0
	global_load_lds_dwordx4 v134, s[44:45]
	s_add_i32 m0, s35, 0x12000
	s_add_u32 s12, s44, 0x10000
	global_load_lds_dwordx4 v130, s[44:45]
	s_addc_u32 s13, s45, 0
	s_add_i32 m0, s35, 0x14000
	v_mov_b32_e32 v131, v135
	global_load_lds_dwordx4 v134, s[12:13]
	s_add_i32 m0, s35, 0x16000
	s_add_u32 s46, s54, s0
	s_addc_u32 s47, s55, s1
	s_add_i32 s58, s35, 0x2000
	global_load_lds_dwordx4 v130, s[12:13]
	s_mov_b32 m0, s35
	s_add_u32 s0, s46, 0x10000
	global_load_lds_dwordx4 v136, s[46:47]
	s_mov_b32 m0, s58
	s_addc_u32 s1, s47, 0
	s_add_i32 s59, s35, 0x4000
	global_load_lds_dwordx4 v132, s[46:47]
	s_mov_b32 m0, s59
	s_add_i32 s60, s35, 0x6000
	global_load_lds_dwordx4 v136, s[0:1]
	s_mov_b32 m0, s60
	v_mov_b32_e32 v137, v135
	global_load_lds_dwordx4 v132, s[0:1]
	v_mov_b32_e32 v133, v135
	s_cmp_eq_u32 s7, 1
	s_mov_b32 s61, 0
	v_lshl_add_u64 v[8:9], s[44:45], 0, v[134:135]
	v_lshl_add_u64 v[6:7], s[44:45], 0, v[130:131]
	v_lshl_add_u64 v[2:3], s[46:47], 0, v[136:137]
	s_cselect_b64 s[0:1], -1, 0
	s_cmp_lg_u32 s7, 1
	v_lshl_add_u64 v[4:5], s[46:47], 0, v[132:133]
	s_cbranch_scc1 .LBB0_2711
	s_barrier
;     __device__ __forceinline__ bool next(int i, Unit& u) const { return (i < na) ? a.next(i, u) : b.next(i - na, u); }
; #define PG8_STAGE(bufoff, gbase, voff) do { _Pragma("unroll") for (int _i = 0; _i < 2; ++_i) \
;         __builtin_amdgcn_global_load_lds((const unsigned*)((const char*)(gbase) + (voff)[_i]), (PG8_LAS unsigned*)(lds + (bufoff) + ldsw + _i * 8192), 16, 0, 0); } while (0)
; #define PG8_WAIT_V(n) asm volatile("s_waitcnt vmcnt(" #n ")" ::: "memory")
; #define PG8_BAR __builtin_amdgcn_s_barrier()
;     __device__ __forceinline__ bool next(int i, Unit& u) const {
;         const long L = (long)first + (long)i * G; if (L >= n) return false;
; template <class Epi, bool ALIGN_EPI = true, bool SP2 = true, bool QUARTER = false, class Sched = Order>
; __device__ __forceinline__ void gemm_phase(PG8_LAS unsigned char* lds, const Gemm g, const Sched& S, const Epi& E) {
;     ...
;         PG8_STAGE(PG8_SB(1, 0), cB + kstep, voffB); PG8_STAGE(PG8_SA(1, 0), cA + kstep, voffA); PG8_STAGE(PG8_SB(1, 1), cB + hstepB + kstep, voffB);
;         PG8_WAIT_V(6); PG8_BAR;
;     } else {
;         PG8_STAGE(PG8_SB(0, 0), cB, voffB); PG8_STAGE(PG8_SA(0, 0), cA, voffA); PG8_STAGE(PG8_SB(0, 1), cB + hstepB, voffB); PG8_STAGE(PG8_SA(0, 1), cA + hstepA, voffA);
;         if (wr == 1) PG8_BAR;
;         PG8_WAIT_V(4); PG8_BAR;
;         PG8_STAGE(PG8_SB(1, 0), cB + kstep, voffB); PG8_STAGE(PG8_SA(1, 0), cA + kstep, voffA); PG8_STAGE(PG8_SB(1, 1), cB + hstepB + kstep, voffB);
;         PG8_WAIT_V(6); PG8_BAR;
;     }
.LBB0_2711:
	s_sub_i32 s62, s4, s33
	s_ashr_i32 s4, s6, 31
	s_lshr_b32 s4, s4, 26
	s_add_i32 s4, s6, s4
	s_ashr_i32 s63, s4, 6
	s_lshl_b32 s4, s5, 5
	s_and_b32 s18, s4, 0x60
	s_mov_b64 s[4:5], 0x80
	s_add_i32 m0, s35, 0x18000
	v_lshl_add_u64 v[8:9], v[8:9], 0, s[4:5]
	s_lshl_b32 s16, s7, 13
	s_lshl_b32 s17, s18, 7
	s_waitcnt vmcnt(2)
	s_barrier
	global_load_lds_dwordx4 v[8:9], off
	v_lshl_add_u64 v[6:7], v[6:7], 0, s[4:5]
	s_add_i32 m0, s35, 0x1a000
	s_add_i32 s64, s35, 0x8000
	s_add_i32 s65, s35, 0xa000
	global_load_lds_dwordx4 v[6:7], off
	v_lshl_add_u64 v[2:3], v[2:3], 0, s[4:5]
	s_mov_b32 m0, s64
	s_add_u32 s12, s44, 0x10080
	global_load_lds_dwordx4 v[2:3], off
	v_lshl_add_u64 v[2:3], v[4:5], 0, s[4:5]
	s_mov_b32 m0, s65
	s_addc_u32 s13, s45, 0
	global_load_lds_dwordx4 v[2:3], off
	s_add_i32 m0, s35, 0x1c000
	v_lshl_add_u64 v[2:3], s[12:13], 0, v[134:135]
	global_load_lds_dwordx4 v[2:3], off
	v_lshl_add_u64 v[2:3], s[12:13], 0, v[130:131]
	s_add_i32 m0, s35, 0x1e000
	s_cmp_gt_i32 s6, 63
	global_load_lds_dwordx4 v[2:3], off
	v_lshrrev_b32_e32 v3, 1, v11
	v_and_b32_e32 v3, 24, v3
	v_and_b32_e32 v2, 15, v11
	v_lshlrev_b32_e32 v4, 1, v3
	v_lshl_or_b32 v1, s7, 6, v2
	v_lshl_or_b32 v2, v2, 6, v4
	v_lshlrev_b32_e32 v4, 2, v11
	v_and_b32_e32 v4, 32, v4
	v_bitop3_b32 v5, v2, s16, v4 bitop3:0xde
	v_bitop3_b32 v146, v2, s17, v4 bitop3:0xde
	v_lshlrev_b32_e32 v2, 12, v10
	v_and_b32_e32 v2, 0xffffe000, v2
	v_or_b32_e32 v147, s18, v3
	v_lshl_add_u32 v2, v12, 9, v2
	v_and_b32_e32 v3, 1, v10
	v_lshl_or_b32 v2, v3, 6, v2
	s_cselect_b64 s[6:7], -1, 0
	s_add_i32 s66, s63, -2
	v_lshl_add_u32 v138, v13, 1, v2
	v_lshlrev_b32_e32 v2, 12, v15
	s_cmpk_lt_u32 s3, 0x100
	v_and_b32_e32 v2, 0xffffe000, v2
	s_waitcnt vmcnt(6)
	s_cselect_b64 s[12:13], -1, 0
	s_add_u32 s16, s40, 0x17200000
	v_lshl_add_u32 v2, v14, 9, v2
	v_and_b32_e32 v3, 1, v15
	s_addc_u32 s17, s41, 0
	v_lshl_or_b32 v2, v3, 6, v2
	s_add_i32 s69, 0, 0x10000
	s_add_i32 s70, 0, 0x14000
	s_sext_i32_i8 s72, s2
	s_ashr_i32 s67, s52, 31
	s_ashr_i32 s68, s62, 31
	v_mov_b32_e32 v139, v135
	v_lshl_add_u32 v140, v16, 1, v2
	v_mov_b32_e32 v141, v135
	s_movk_i32 s98, 0x104
	s_cmp_gt_i32 s52, 0x103
	s_cselect_b32 s98, 0x108, s98
	s_add_i32 s99, s98, -1
	v_mov_b32_e32 v142, s98
	v_mov_b32_e32 v143, 0
	v_mov_b32_e32 v144, s99
	v_mov_b32_e32 v145, 0
	v_add_u32_e32 v148, s69, v146
	v_add_u32_e32 v149, s70, v146
	v_add_u32_e32 v150, 0, v5
	s_mov_b32 s71, 0x17200000
	s_mov_b64 s[18:19], 0x40000
	s_mov_b64 s[20:21], 0x48000
	s_mov_b64 s[24:25], 0x50000
	s_mov_b64 s[26:27], 0x58000
	s_barrier
	s_branch .LBB0_2714
